# v50 plus gelu polynomial fmaak pairs merged into v_pk_fma_f32 with VGPR constant pairs
# baseline (speedup 1.0000x reference)
; __device__ __forceinline__ unsigned cvt_pk_bf16(float lo, float hi) { unsigned r; asm volatile("v_cvt_pk_bf16_f32 %0, %1, %2" : "=v"(r) : "v"(lo), "v"(hi)); return r; }
; __device__ __forceinline__ float sigmoid_f(float x) { return __builtin_amdgcn_rcpf(1.0f + __builtin_amdgcn_exp2f(-1.4426950409f * x)); }
;     __device__ __forceinline__ void operator()(f32x4 (&acc)[2][2][4][2], const Unit& u, int wr, int wc, int fr, int fq) const {
;     ...
;                 for (int m = 0; m < 4; ++m) { bf16_t* rowp = O + (size_t)(row0 + ai * HALF + m * 16) * LDP + col0;
;                     float v[8];
; #pragma unroll
;                     for (int j = 0; j < 8; ++j) {
;                         const float x0 = acc[ai][0][m][j >> 2][j & 3], x1 = acc[ai][1][m][j >> 2][j & 3];
;                         const float f0 = (mode == 4) ? x0 * sigmoid_f(1.5957691216f * (x0 + 0.044715f * x0 * x0 * x0)) : x0;
;                         const float f1 = (mode == 5) ? x1 : x1 * sigmoid_f(x1);
;                         v[j] = f0 * f1;
;                     }
;                     u32x4 w; w.x = cvt_pk_bf16(v[0], v[1]); w.y = cvt_pk_bf16(v[2], v[3]); w.z = cvt_pk_bf16(v[4], v[5]); w.w = cvt_pk_bf16(v[6], v[7]);
;                     *(u32x4*)rowp = w; }
.Lp1_epi_m4:
	s_lshl_b32 s14, s59, 8
	s_add_u32 s24, s24, s14
	s_addc_u32 s25, s25, 0
	v_mov_b32_e32 v151, 0xbdd2d3e8
	v_mov_b32_e32 v148, 0xbdd2d3e8
	v_mov_b32_e32 v149, 0xbdd2d3e8
	v_mov_b32_e32 v160, 0xc0135761
	v_mov_b32_e32 v161, 0xc0135761
	v_pk_mul_f32 v[152:153], v[124:125], v[124:125]
	v_pk_mul_f32 v[154:155], v[126:127], v[126:127]
	v_pk_mul_f32 v[156:157], v[120:121], v[120:121]
	v_pk_mul_f32 v[158:159], v[122:123], v[122:123]
	v_pk_mul_f32 v[168:169], v[116:117], s[62:63]
	v_pk_mul_f32 v[170:171], v[118:119], s[62:63]
	v_pk_mul_f32 v[172:173], v[112:113], s[62:63]
	v_pk_mul_f32 v[174:175], v[114:115], s[62:63]
	v_pk_fma_f32 v[152:153], v[148:149], v[152:153], v[160:161]
	v_pk_fma_f32 v[154:155], v[148:149], v[154:155], v[160:161]
	v_pk_fma_f32 v[156:157], v[148:149], v[156:157], v[160:161]
	v_pk_fma_f32 v[158:159], v[148:149], v[158:159], v[160:161]
	v_exp_f32_e32 v168, v168
	v_exp_f32_e32 v169, v169
	v_exp_f32_e32 v170, v170
	v_exp_f32_e32 v171, v171
	v_exp_f32_e32 v172, v172
	v_exp_f32_e32 v173, v173
	v_exp_f32_e32 v174, v174
	v_exp_f32_e32 v175, v175
	v_pk_mul_f32 v[152:153], v[124:125], v[152:153]
	v_pk_mul_f32 v[154:155], v[126:127], v[154:155]
	v_pk_mul_f32 v[156:157], v[120:121], v[156:157]
	v_pk_mul_f32 v[158:159], v[122:123], v[158:159]
	v_exp_f32_e32 v152, v152
	v_exp_f32_e32 v153, v153
	v_exp_f32_e32 v154, v154
	v_exp_f32_e32 v155, v155
	v_exp_f32_e32 v156, v156
	v_exp_f32_e32 v157, v157
	v_exp_f32_e32 v158, v158
	v_exp_f32_e32 v159, v159
	v_pk_add_f32 v[168:169], v[168:169], s[64:65]
	v_pk_add_f32 v[170:171], v[170:171], s[64:65]
	v_pk_add_f32 v[172:173], v[172:173], s[64:65]
	v_pk_add_f32 v[174:175], v[174:175], s[64:65]
	v_pk_fma_f32 v[152:153], v[152:153], v[168:169], v[168:169]
	v_pk_fma_f32 v[154:155], v[154:155], v[170:171], v[170:171]
	v_pk_fma_f32 v[156:157], v[156:157], v[172:173], v[172:173]
	v_pk_fma_f32 v[158:159], v[158:159], v[174:175], v[174:175]
	v_pk_mul_f32 v[168:169], v[124:125], v[116:117]
	v_pk_mul_f32 v[170:171], v[126:127], v[118:119]
	v_pk_mul_f32 v[172:173], v[120:121], v[112:113]
	v_pk_mul_f32 v[174:175], v[122:123], v[114:115]
	v_rcp_f32_e32 v152, v152
	v_rcp_f32_e32 v153, v153
	v_rcp_f32_e32 v154, v154
	v_rcp_f32_e32 v155, v155
	v_rcp_f32_e32 v156, v156
	v_rcp_f32_e32 v157, v157
	v_rcp_f32_e32 v158, v158
	v_rcp_f32_e32 v159, v159
	s_nop 0
	v_pk_mul_f32 v[152:153], v[168:169], v[152:153]
	v_pk_mul_f32 v[154:155], v[170:171], v[154:155]
	v_pk_mul_f32 v[156:157], v[172:173], v[156:157]
	v_pk_mul_f32 v[158:159], v[174:175], v[158:159]
	v_cvt_pk_bf16_f32 v176, v152, v153
	v_cvt_pk_bf16_f32 v177, v154, v155
	v_cvt_pk_bf16_f32 v178, v156, v157
	v_cvt_pk_bf16_f32 v179, v158, v159
	global_store_dwordx4 v150, v[176:179], s[24:25]
	s_add_u32 s24, s24, 0x8000
	s_addc_u32 s25, s25, 0
	v_pk_mul_f32 v[152:153], v[108:109], v[108:109]
	v_pk_mul_f32 v[154:155], v[110:111], v[110:111]
	v_pk_mul_f32 v[156:157], v[104:105], v[104:105]
	v_pk_mul_f32 v[158:159], v[106:107], v[106:107]
	v_pk_mul_f32 v[168:169], v[100:101], s[62:63]
	v_pk_mul_f32 v[170:171], v[102:103], s[62:63]
	v_pk_mul_f32 v[172:173], v[96:97], s[62:63]
	v_pk_mul_f32 v[174:175], v[98:99], s[62:63]
	v_pk_fma_f32 v[152:153], v[148:149], v[152:153], v[160:161]
	v_pk_fma_f32 v[154:155], v[148:149], v[154:155], v[160:161]
	v_pk_fma_f32 v[156:157], v[148:149], v[156:157], v[160:161]
	v_pk_fma_f32 v[158:159], v[148:149], v[158:159], v[160:161]
	v_exp_f32_e32 v168, v168
	v_exp_f32_e32 v169, v169
	v_exp_f32_e32 v170, v170
	v_exp_f32_e32 v171, v171
	v_exp_f32_e32 v172, v172
	v_exp_f32_e32 v173, v173
	v_exp_f32_e32 v174, v174
	v_exp_f32_e32 v175, v175
	v_pk_mul_f32 v[152:153], v[108:109], v[152:153]
	v_pk_mul_f32 v[154:155], v[110:111], v[154:155]
	v_pk_mul_f32 v[156:157], v[104:105], v[156:157]
	v_pk_mul_f32 v[158:159], v[106:107], v[158:159]
	v_exp_f32_e32 v152, v152
	v_exp_f32_e32 v153, v153
	v_exp_f32_e32 v154, v154
	v_exp_f32_e32 v155, v155
	v_exp_f32_e32 v156, v156
	v_exp_f32_e32 v157, v157
	v_exp_f32_e32 v158, v158
	v_exp_f32_e32 v159, v159
	v_pk_add_f32 v[168:169], v[168:169], s[64:65]
	v_pk_add_f32 v[170:171], v[170:171], s[64:65]
	v_pk_add_f32 v[172:173], v[172:173], s[64:65]
	v_pk_add_f32 v[174:175], v[174:175], s[64:65]
	v_pk_fma_f32 v[152:153], v[152:153], v[168:169], v[168:169]
	v_pk_fma_f32 v[154:155], v[154:155], v[170:171], v[170:171]
	v_pk_fma_f32 v[156:157], v[156:157], v[172:173], v[172:173]
	v_pk_fma_f32 v[158:159], v[158:159], v[174:175], v[174:175]
	v_pk_mul_f32 v[168:169], v[108:109], v[100:101]
	v_pk_mul_f32 v[170:171], v[110:111], v[102:103]
	v_pk_mul_f32 v[172:173], v[104:105], v[96:97]
	v_pk_mul_f32 v[174:175], v[106:107], v[98:99]
	v_rcp_f32_e32 v152, v152
	v_rcp_f32_e32 v153, v153
	v_rcp_f32_e32 v154, v154
	v_rcp_f32_e32 v155, v155
	v_rcp_f32_e32 v156, v156
	v_rcp_f32_e32 v157, v157
	v_rcp_f32_e32 v158, v158
	v_rcp_f32_e32 v159, v159
	s_nop 0
	v_pk_mul_f32 v[152:153], v[168:169], v[152:153]
	v_pk_mul_f32 v[154:155], v[170:171], v[154:155]
	v_pk_mul_f32 v[156:157], v[172:173], v[156:157]
	v_pk_mul_f32 v[158:159], v[174:175], v[158:159]
	v_cvt_pk_bf16_f32 v180, v152, v153
	v_cvt_pk_bf16_f32 v181, v154, v155
	v_cvt_pk_bf16_f32 v182, v156, v157
	v_cvt_pk_bf16_f32 v183, v158, v159
	global_store_dwordx4 v150, v[180:183], s[24:25]
	s_add_u32 s24, s24, 0x8000
	s_addc_u32 s25, s25, 0
	v_pk_mul_f32 v[152:153], v[92:93], v[92:93]
	v_pk_mul_f32 v[154:155], v[94:95], v[94:95]
	v_pk_mul_f32 v[156:157], v[88:89], v[88:89]
	v_pk_mul_f32 v[158:159], v[90:91], v[90:91]
	v_pk_mul_f32 v[168:169], v[84:85], s[62:63]
	v_pk_mul_f32 v[170:171], v[86:87], s[62:63]
	v_pk_mul_f32 v[172:173], v[80:81], s[62:63]
	v_pk_mul_f32 v[174:175], v[82:83], s[62:63]
; __device__ __forceinline__ unsigned cvt_pk_bf16(float lo, float hi) { unsigned r; asm volatile("v_cvt_pk_bf16_f32 %0, %1, %2" : "=v"(r) : "v"(lo), "v"(hi)); return r; }
; __device__ __forceinline__ float sigmoid_f(float x) { return __builtin_amdgcn_rcpf(1.0f + __builtin_amdgcn_exp2f(-1.4426950409f * x)); }
;     __device__ __forceinline__ void operator()(f32x4 (&acc)[2][2][4][2], const Unit& u, int wr, int wc, int fr, int fq) const {
;     ...
;                 for (int m = 0; m < 4; ++m) { bf16_t* rowp = O + (size_t)(row0 + ai * HALF + m * 16) * LDP + col0;
;                     float v[8];
; #pragma unroll
;                     for (int j = 0; j < 8; ++j) {
;                         const float x0 = acc[ai][0][m][j >> 2][j & 3], x1 = acc[ai][1][m][j >> 2][j & 3];
;                         const float f0 = (mode == 4) ? x0 * sigmoid_f(1.5957691216f * (x0 + 0.044715f * x0 * x0 * x0)) : x0;
;                         const float f1 = (mode == 5) ? x1 : x1 * sigmoid_f(x1);
;                         v[j] = f0 * f1;
;                     }
;                     u32x4 w; w.x = cvt_pk_bf16(v[0], v[1]); w.y = cvt_pk_bf16(v[2], v[3]); w.z = cvt_pk_bf16(v[4], v[5]); w.w = cvt_pk_bf16(v[6], v[7]);
;                     *(u32x4*)rowp = w; }
	v_pk_fma_f32 v[152:153], v[148:149], v[152:153], v[160:161]
	v_pk_fma_f32 v[154:155], v[148:149], v[154:155], v[160:161]
	v_pk_fma_f32 v[156:157], v[148:149], v[156:157], v[160:161]
	v_pk_fma_f32 v[158:159], v[148:149], v[158:159], v[160:161]
	v_exp_f32_e32 v168, v168
	v_exp_f32_e32 v169, v169
	v_exp_f32_e32 v170, v170
	v_exp_f32_e32 v171, v171
	v_exp_f32_e32 v172, v172
	v_exp_f32_e32 v173, v173
	v_exp_f32_e32 v174, v174
	v_exp_f32_e32 v175, v175
	v_pk_mul_f32 v[152:153], v[92:93], v[152:153]
	v_pk_mul_f32 v[154:155], v[94:95], v[154:155]
	v_pk_mul_f32 v[156:157], v[88:89], v[156:157]
	v_pk_mul_f32 v[158:159], v[90:91], v[158:159]
	v_exp_f32_e32 v152, v152
	v_exp_f32_e32 v153, v153
	v_exp_f32_e32 v154, v154
	v_exp_f32_e32 v155, v155
	v_exp_f32_e32 v156, v156
	v_exp_f32_e32 v157, v157
	v_exp_f32_e32 v158, v158
	v_exp_f32_e32 v159, v159
	v_pk_add_f32 v[168:169], v[168:169], s[64:65]
	v_pk_add_f32 v[170:171], v[170:171], s[64:65]
	v_pk_add_f32 v[172:173], v[172:173], s[64:65]
	v_pk_add_f32 v[174:175], v[174:175], s[64:65]
	v_pk_fma_f32 v[152:153], v[152:153], v[168:169], v[168:169]
	v_pk_fma_f32 v[154:155], v[154:155], v[170:171], v[170:171]
	v_pk_fma_f32 v[156:157], v[156:157], v[172:173], v[172:173]
	v_pk_fma_f32 v[158:159], v[158:159], v[174:175], v[174:175]
	v_pk_mul_f32 v[168:169], v[92:93], v[84:85]
	v_pk_mul_f32 v[170:171], v[94:95], v[86:87]
	v_pk_mul_f32 v[172:173], v[88:89], v[80:81]
	v_pk_mul_f32 v[174:175], v[90:91], v[82:83]
	v_rcp_f32_e32 v152, v152
	v_rcp_f32_e32 v153, v153
	v_rcp_f32_e32 v154, v154
	v_rcp_f32_e32 v155, v155
	v_rcp_f32_e32 v156, v156
	v_rcp_f32_e32 v157, v157
	v_rcp_f32_e32 v158, v158
	v_rcp_f32_e32 v159, v159
	s_nop 0
	v_pk_mul_f32 v[152:153], v[168:169], v[152:153]
	v_pk_mul_f32 v[154:155], v[170:171], v[154:155]
	v_pk_mul_f32 v[156:157], v[172:173], v[156:157]
	v_pk_mul_f32 v[158:159], v[174:175], v[158:159]
	v_cvt_pk_bf16_f32 v176, v152, v153
	v_cvt_pk_bf16_f32 v177, v154, v155
	v_cvt_pk_bf16_f32 v178, v156, v157
	v_cvt_pk_bf16_f32 v179, v158, v159
	global_store_dwordx4 v150, v[176:179], s[24:25]
	s_add_u32 s24, s24, 0x8000
	s_addc_u32 s25, s25, 0
	v_pk_mul_f32 v[152:153], v[76:77], v[76:77]
	v_pk_mul_f32 v[154:155], v[78:79], v[78:79]
	v_pk_mul_f32 v[156:157], v[72:73], v[72:73]
	v_pk_mul_f32 v[158:159], v[74:75], v[74:75]
	v_pk_mul_f32 v[168:169], v[68:69], s[62:63]
	v_pk_mul_f32 v[170:171], v[70:71], s[62:63]
	v_pk_mul_f32 v[172:173], v[64:65], s[62:63]
	v_pk_mul_f32 v[174:175], v[66:67], s[62:63]
	v_pk_fma_f32 v[152:153], v[148:149], v[152:153], v[160:161]
	v_pk_fma_f32 v[154:155], v[148:149], v[154:155], v[160:161]
	v_pk_fma_f32 v[156:157], v[148:149], v[156:157], v[160:161]
	v_pk_fma_f32 v[158:159], v[148:149], v[158:159], v[160:161]
	v_exp_f32_e32 v168, v168
	v_exp_f32_e32 v169, v169
	v_exp_f32_e32 v170, v170
	v_exp_f32_e32 v171, v171
	v_exp_f32_e32 v172, v172
	v_exp_f32_e32 v173, v173
	v_exp_f32_e32 v174, v174
	v_exp_f32_e32 v175, v175
	v_pk_mul_f32 v[152:153], v[76:77], v[152:153]
	v_pk_mul_f32 v[154:155], v[78:79], v[154:155]
	v_pk_mul_f32 v[156:157], v[72:73], v[156:157]
	v_pk_mul_f32 v[158:159], v[74:75], v[158:159]
	v_exp_f32_e32 v152, v152
	v_exp_f32_e32 v153, v153
	v_exp_f32_e32 v154, v154
	v_exp_f32_e32 v155, v155
	v_exp_f32_e32 v156, v156
	v_exp_f32_e32 v157, v157
	v_exp_f32_e32 v158, v158
	v_exp_f32_e32 v159, v159
	v_pk_add_f32 v[168:169], v[168:169], s[64:65]
	v_pk_add_f32 v[170:171], v[170:171], s[64:65]
	v_pk_add_f32 v[172:173], v[172:173], s[64:65]
	v_pk_add_f32 v[174:175], v[174:175], s[64:65]
	v_pk_fma_f32 v[152:153], v[152:153], v[168:169], v[168:169]
	v_pk_fma_f32 v[154:155], v[154:155], v[170:171], v[170:171]
	v_pk_fma_f32 v[156:157], v[156:157], v[172:173], v[172:173]
	v_pk_fma_f32 v[158:159], v[158:159], v[174:175], v[174:175]
	v_pk_mul_f32 v[168:169], v[76:77], v[68:69]
	v_pk_mul_f32 v[170:171], v[78:79], v[70:71]
	v_pk_mul_f32 v[172:173], v[72:73], v[64:65]
	v_pk_mul_f32 v[174:175], v[74:75], v[66:67]
	v_rcp_f32_e32 v152, v152
	v_rcp_f32_e32 v153, v153
	v_rcp_f32_e32 v154, v154
	v_rcp_f32_e32 v155, v155
	v_rcp_f32_e32 v156, v156
	v_rcp_f32_e32 v157, v157
	v_rcp_f32_e32 v158, v158
	v_rcp_f32_e32 v159, v159
	s_nop 0
	v_pk_mul_f32 v[152:153], v[168:169], v[152:153]
	v_pk_mul_f32 v[154:155], v[170:171], v[154:155]
	v_pk_mul_f32 v[156:157], v[172:173], v[156:157]
	v_pk_mul_f32 v[158:159], v[174:175], v[158:159]
	v_cvt_pk_bf16_f32 v180, v152, v153
	v_cvt_pk_bf16_f32 v181, v154, v155
	v_cvt_pk_bf16_f32 v182, v156, v157
	v_cvt_pk_bf16_f32 v183, v158, v159
	global_store_dwordx4 v150, v[180:183], s[24:25]
	s_add_u32 s24, s24, 0x28000
	s_addc_u32 s25, s25, 0
	v_pk_mul_f32 v[152:153], v[60:61], v[60:61]
	v_pk_mul_f32 v[154:155], v[62:63], v[62:63]
	v_pk_mul_f32 v[156:157], v[56:57], v[56:57]
	v_pk_mul_f32 v[158:159], v[58:59], v[58:59]
	v_pk_mul_f32 v[168:169], v[52:53], s[62:63]
	v_pk_mul_f32 v[170:171], v[54:55], s[62:63]
	v_pk_mul_f32 v[172:173], v[48:49], s[62:63]
	v_pk_mul_f32 v[174:175], v[50:51], s[62:63]
	v_pk_fma_f32 v[152:153], v[148:149], v[152:153], v[160:161]
	v_pk_fma_f32 v[154:155], v[148:149], v[154:155], v[160:161]
	v_pk_fma_f32 v[156:157], v[148:149], v[156:157], v[160:161]
	v_pk_fma_f32 v[158:159], v[148:149], v[158:159], v[160:161]
	v_exp_f32_e32 v168, v168
	v_exp_f32_e32 v169, v169
	v_exp_f32_e32 v170, v170
	v_exp_f32_e32 v171, v171
	v_exp_f32_e32 v172, v172
	v_exp_f32_e32 v173, v173
	v_exp_f32_e32 v174, v174
	v_exp_f32_e32 v175, v175
	v_pk_mul_f32 v[152:153], v[60:61], v[152:153]
	v_pk_mul_f32 v[154:155], v[62:63], v[154:155]
	v_pk_mul_f32 v[156:157], v[56:57], v[156:157]
	v_pk_mul_f32 v[158:159], v[58:59], v[158:159]
	v_exp_f32_e32 v152, v152
	v_exp_f32_e32 v153, v153
; __device__ __forceinline__ unsigned cvt_pk_bf16(float lo, float hi) { unsigned r; asm volatile("v_cvt_pk_bf16_f32 %0, %1, %2" : "=v"(r) : "v"(lo), "v"(hi)); return r; }
; __device__ __forceinline__ float sigmoid_f(float x) { return __builtin_amdgcn_rcpf(1.0f + __builtin_amdgcn_exp2f(-1.4426950409f * x)); }
;     __device__ __forceinline__ void operator()(f32x4 (&acc)[2][2][4][2], const Unit& u, int wr, int wc, int fr, int fq) const {
;     ...
;                 for (int m = 0; m < 4; ++m) { bf16_t* rowp = O + (size_t)(row0 + ai * HALF + m * 16) * LDP + col0;
;                     float v[8];
; #pragma unroll
;                     for (int j = 0; j < 8; ++j) {
;                         const float x0 = acc[ai][0][m][j >> 2][j & 3], x1 = acc[ai][1][m][j >> 2][j & 3];
;                         const float f0 = (mode == 4) ? x0 * sigmoid_f(1.5957691216f * (x0 + 0.044715f * x0 * x0 * x0)) : x0;
;                         const float f1 = (mode == 5) ? x1 : x1 * sigmoid_f(x1);
;                         v[j] = f0 * f1;
;                     }
;                     u32x4 w; w.x = cvt_pk_bf16(v[0], v[1]); w.y = cvt_pk_bf16(v[2], v[3]); w.z = cvt_pk_bf16(v[4], v[5]); w.w = cvt_pk_bf16(v[6], v[7]);
;                     *(u32x4*)rowp = w; }
	v_exp_f32_e32 v154, v154
	v_exp_f32_e32 v155, v155
	v_exp_f32_e32 v156, v156
	v_exp_f32_e32 v157, v157
	v_exp_f32_e32 v158, v158
	v_exp_f32_e32 v159, v159
	v_pk_add_f32 v[168:169], v[168:169], s[64:65]
	v_pk_add_f32 v[170:171], v[170:171], s[64:65]
	v_pk_add_f32 v[172:173], v[172:173], s[64:65]
	v_pk_add_f32 v[174:175], v[174:175], s[64:65]
	v_pk_fma_f32 v[152:153], v[152:153], v[168:169], v[168:169]
	v_pk_fma_f32 v[154:155], v[154:155], v[170:171], v[170:171]
	v_pk_fma_f32 v[156:157], v[156:157], v[172:173], v[172:173]
	v_pk_fma_f32 v[158:159], v[158:159], v[174:175], v[174:175]
	v_pk_mul_f32 v[168:169], v[60:61], v[52:53]
	v_pk_mul_f32 v[170:171], v[62:63], v[54:55]
	v_pk_mul_f32 v[172:173], v[56:57], v[48:49]
	v_pk_mul_f32 v[174:175], v[58:59], v[50:51]
	v_rcp_f32_e32 v152, v152
	v_rcp_f32_e32 v153, v153
	v_rcp_f32_e32 v154, v154
	v_rcp_f32_e32 v155, v155
	v_rcp_f32_e32 v156, v156
	v_rcp_f32_e32 v157, v157
	v_rcp_f32_e32 v158, v158
	v_rcp_f32_e32 v159, v159
	s_nop 0
	v_pk_mul_f32 v[152:153], v[168:169], v[152:153]
	v_pk_mul_f32 v[154:155], v[170:171], v[154:155]
	v_pk_mul_f32 v[156:157], v[172:173], v[156:157]
	v_pk_mul_f32 v[158:159], v[174:175], v[158:159]
	v_cvt_pk_bf16_f32 v176, v152, v153
	v_cvt_pk_bf16_f32 v177, v154, v155
	v_cvt_pk_bf16_f32 v178, v156, v157
	v_cvt_pk_bf16_f32 v179, v158, v159
	global_store_dwordx4 v150, v[176:179], s[24:25]
	s_add_u32 s24, s24, 0x8000
	s_addc_u32 s25, s25, 0
	v_pk_mul_f32 v[152:153], v[44:45], v[44:45]
	v_pk_mul_f32 v[154:155], v[46:47], v[46:47]
	v_pk_mul_f32 v[156:157], v[40:41], v[40:41]
	v_pk_mul_f32 v[158:159], v[42:43], v[42:43]
	v_pk_mul_f32 v[168:169], v[36:37], s[62:63]
	v_pk_mul_f32 v[170:171], v[38:39], s[62:63]
	v_pk_mul_f32 v[172:173], v[32:33], s[62:63]
	v_pk_mul_f32 v[174:175], v[34:35], s[62:63]
	v_pk_fma_f32 v[152:153], v[148:149], v[152:153], v[160:161]
	v_pk_fma_f32 v[154:155], v[148:149], v[154:155], v[160:161]
	v_pk_fma_f32 v[156:157], v[148:149], v[156:157], v[160:161]
	v_pk_fma_f32 v[158:159], v[148:149], v[158:159], v[160:161]
	v_exp_f32_e32 v168, v168
	v_exp_f32_e32 v169, v169
	v_exp_f32_e32 v170, v170
	v_exp_f32_e32 v171, v171
	v_exp_f32_e32 v172, v172
	v_exp_f32_e32 v173, v173
	v_exp_f32_e32 v174, v174
	v_exp_f32_e32 v175, v175
	v_pk_mul_f32 v[152:153], v[44:45], v[152:153]
	v_pk_mul_f32 v[154:155], v[46:47], v[154:155]
	v_pk_mul_f32 v[156:157], v[40:41], v[156:157]
	v_pk_mul_f32 v[158:159], v[42:43], v[158:159]
	v_exp_f32_e32 v152, v152
	v_exp_f32_e32 v153, v153
	v_exp_f32_e32 v154, v154
	v_exp_f32_e32 v155, v155
	v_exp_f32_e32 v156, v156
	v_exp_f32_e32 v157, v157
	v_exp_f32_e32 v158, v158
	v_exp_f32_e32 v159, v159
	v_pk_add_f32 v[168:169], v[168:169], s[64:65]
	v_pk_add_f32 v[170:171], v[170:171], s[64:65]
	v_pk_add_f32 v[172:173], v[172:173], s[64:65]
	v_pk_add_f32 v[174:175], v[174:175], s[64:65]
	v_pk_fma_f32 v[152:153], v[152:153], v[168:169], v[168:169]
	v_pk_fma_f32 v[154:155], v[154:155], v[170:171], v[170:171]
	v_pk_fma_f32 v[156:157], v[156:157], v[172:173], v[172:173]
	v_pk_fma_f32 v[158:159], v[158:159], v[174:175], v[174:175]
	v_pk_mul_f32 v[168:169], v[44:45], v[36:37]
	v_pk_mul_f32 v[170:171], v[46:47], v[38:39]
	v_pk_mul_f32 v[172:173], v[40:41], v[32:33]
	v_pk_mul_f32 v[174:175], v[42:43], v[34:35]
	v_rcp_f32_e32 v152, v152
	v_rcp_f32_e32 v153, v153
	v_rcp_f32_e32 v154, v154
	v_rcp_f32_e32 v155, v155
	v_rcp_f32_e32 v156, v156
	v_rcp_f32_e32 v157, v157
	v_rcp_f32_e32 v158, v158
	v_rcp_f32_e32 v159, v159
	s_nop 0
	v_pk_mul_f32 v[152:153], v[168:169], v[152:153]
	v_pk_mul_f32 v[154:155], v[170:171], v[154:155]
	v_pk_mul_f32 v[156:157], v[172:173], v[156:157]
	v_pk_mul_f32 v[158:159], v[174:175], v[158:159]
	v_cvt_pk_bf16_f32 v180, v152, v153
	v_cvt_pk_bf16_f32 v181, v154, v155
	v_cvt_pk_bf16_f32 v182, v156, v157
	v_cvt_pk_bf16_f32 v183, v158, v159
	global_store_dwordx4 v150, v[180:183], s[24:25]
	s_add_u32 s24, s24, 0x8000
	s_addc_u32 s25, s25, 0
	v_pk_mul_f32 v[152:153], v[28:29], v[28:29]
	v_pk_mul_f32 v[154:155], v[30:31], v[30:31]
	v_pk_mul_f32 v[156:157], v[24:25], v[24:25]
	v_pk_mul_f32 v[158:159], v[26:27], v[26:27]
	v_pk_mul_f32 v[168:169], v[20:21], s[62:63]
	v_pk_mul_f32 v[170:171], v[22:23], s[62:63]
	v_pk_mul_f32 v[172:173], v[16:17], s[62:63]
	v_pk_mul_f32 v[174:175], v[18:19], s[62:63]
	v_pk_fma_f32 v[152:153], v[148:149], v[152:153], v[160:161]
	v_pk_fma_f32 v[154:155], v[148:149], v[154:155], v[160:161]
	v_pk_fma_f32 v[156:157], v[148:149], v[156:157], v[160:161]
	v_pk_fma_f32 v[158:159], v[148:149], v[158:159], v[160:161]
	v_exp_f32_e32 v168, v168
	v_exp_f32_e32 v169, v169
	v_exp_f32_e32 v170, v170
	v_exp_f32_e32 v171, v171
	v_exp_f32_e32 v172, v172
	v_exp_f32_e32 v173, v173
	v_exp_f32_e32 v174, v174
	v_exp_f32_e32 v175, v175
	v_pk_mul_f32 v[152:153], v[28:29], v[152:153]
	v_pk_mul_f32 v[154:155], v[30:31], v[154:155]
	v_pk_mul_f32 v[156:157], v[24:25], v[156:157]
	v_pk_mul_f32 v[158:159], v[26:27], v[158:159]
	v_exp_f32_e32 v152, v152
	v_exp_f32_e32 v153, v153
	v_exp_f32_e32 v154, v154
	v_exp_f32_e32 v155, v155
	v_exp_f32_e32 v156, v156
	v_exp_f32_e32 v157, v157
	v_exp_f32_e32 v158, v158
	v_exp_f32_e32 v159, v159
	v_pk_add_f32 v[168:169], v[168:169], s[64:65]
	v_pk_add_f32 v[170:171], v[170:171], s[64:65]
	v_pk_add_f32 v[172:173], v[172:173], s[64:65]
	v_pk_add_f32 v[174:175], v[174:175], s[64:65]
	v_pk_fma_f32 v[152:153], v[152:153], v[168:169], v[168:169]
	v_pk_fma_f32 v[154:155], v[154:155], v[170:171], v[170:171]
	v_pk_fma_f32 v[156:157], v[156:157], v[172:173], v[172:173]
	v_pk_fma_f32 v[158:159], v[158:159], v[174:175], v[174:175]
	v_pk_mul_f32 v[168:169], v[28:29], v[20:21]
	v_pk_mul_f32 v[170:171], v[30:31], v[22:23]
; __device__ __forceinline__ unsigned cvt_pk_bf16(float lo, float hi) { unsigned r; asm volatile("v_cvt_pk_bf16_f32 %0, %1, %2" : "=v"(r) : "v"(lo), "v"(hi)); return r; }
; __device__ __forceinline__ float sigmoid_f(float x) { return __builtin_amdgcn_rcpf(1.0f + __builtin_amdgcn_exp2f(-1.4426950409f * x)); }
;     __device__ __forceinline__ void operator()(f32x4 (&acc)[2][2][4][2], const Unit& u, int wr, int wc, int fr, int fq) const {
;     ...
;                 for (int m = 0; m < 4; ++m) { bf16_t* rowp = O + (size_t)(row0 + ai * HALF + m * 16) * LDP + col0;
;                     float v[8];
; #pragma unroll
;                     for (int j = 0; j < 8; ++j) {
;                         const float x0 = acc[ai][0][m][j >> 2][j & 3], x1 = acc[ai][1][m][j >> 2][j & 3];
;                         const float f0 = (mode == 4) ? x0 * sigmoid_f(1.5957691216f * (x0 + 0.044715f * x0 * x0 * x0)) : x0;
;                         const float f1 = (mode == 5) ? x1 : x1 * sigmoid_f(x1);
;                         v[j] = f0 * f1;
;                     }
;                     u32x4 w; w.x = cvt_pk_bf16(v[0], v[1]); w.y = cvt_pk_bf16(v[2], v[3]); w.z = cvt_pk_bf16(v[4], v[5]); w.w = cvt_pk_bf16(v[6], v[7]);
;                     *(u32x4*)rowp = w; }
;     ...
;                 for (int m = 0; m < 4; ++m) { bf16_t* rowp = O + (size_t)(row0 + ai * HALF + m * 16) * LDP + col0;
; #pragma unroll
;                     for (int bj = 0; bj < 2; ++bj) {
;                         float v[8];
; #pragma unroll
;                         for (int j = 0; j < 4; ++j) { v[j] = acc[ai][bj][m][0][j]; v[4 + j] = acc[ai][bj][m][1][j]; }
;                         if (mode != 0) {
; #pragma unroll
;                             for (int j = 0; j < 8; ++j) {
;                                 const float x = v[j];
;                                 const float a = (mode == 1) ? 1.5957691216f * (x + 0.044715f * x * x * x) : x;
;                                 const float sg = sigmoid_f(a);
;                                 v[j] = (mode == 3) ? sg : x * sg;
;                             }
;                         }
;                         u32x4 w; w.x = cvt_pk_bf16(v[0], v[1]); w.y = cvt_pk_bf16(v[2], v[3]); w.z = cvt_pk_bf16(v[4], v[5]); w.w = cvt_pk_bf16(v[6], v[7]);
;                         *(u32x4*)(rowp + bj * HALF) = w; } }
	v_pk_mul_f32 v[172:173], v[24:25], v[16:17]
	v_pk_mul_f32 v[174:175], v[26:27], v[18:19]
	v_rcp_f32_e32 v152, v152
	v_rcp_f32_e32 v153, v153
	v_rcp_f32_e32 v154, v154
	v_rcp_f32_e32 v155, v155
	v_rcp_f32_e32 v156, v156
	v_rcp_f32_e32 v157, v157
	v_rcp_f32_e32 v158, v158
	v_rcp_f32_e32 v159, v159
	s_nop 0
	v_pk_mul_f32 v[152:153], v[168:169], v[152:153]
	v_pk_mul_f32 v[154:155], v[170:171], v[154:155]
	v_pk_mul_f32 v[156:157], v[172:173], v[156:157]
	v_pk_mul_f32 v[158:159], v[174:175], v[158:159]
	v_cvt_pk_bf16_f32 v176, v152, v153
	v_cvt_pk_bf16_f32 v177, v154, v155
	v_cvt_pk_bf16_f32 v178, v156, v157
	v_cvt_pk_bf16_f32 v179, v158, v159
	global_store_dwordx4 v150, v[176:179], s[24:25]
	s_add_u32 s24, s24, 0x8000
	s_addc_u32 s25, s25, 0
	v_pk_mul_f32 v[152:153], v[12:13], v[12:13]
	v_pk_mul_f32 v[154:155], v[14:15], v[14:15]
	v_pk_mul_f32 v[156:157], v[8:9], v[8:9]
	v_pk_mul_f32 v[158:159], v[10:11], v[10:11]
	v_pk_mul_f32 v[168:169], v[4:5], s[62:63]
	v_pk_mul_f32 v[170:171], v[6:7], s[62:63]
	v_pk_mul_f32 v[172:173], v[0:1], s[62:63]
	v_pk_mul_f32 v[174:175], v[2:3], s[62:63]
	v_pk_fma_f32 v[152:153], v[148:149], v[152:153], v[160:161]
	v_pk_fma_f32 v[154:155], v[148:149], v[154:155], v[160:161]
	v_pk_fma_f32 v[156:157], v[148:149], v[156:157], v[160:161]
	v_pk_fma_f32 v[158:159], v[148:149], v[158:159], v[160:161]
	v_exp_f32_e32 v168, v168
	v_exp_f32_e32 v169, v169
	v_exp_f32_e32 v170, v170
	v_exp_f32_e32 v171, v171
	v_exp_f32_e32 v172, v172
	v_exp_f32_e32 v173, v173
	v_exp_f32_e32 v174, v174
	v_exp_f32_e32 v175, v175
	v_pk_mul_f32 v[152:153], v[12:13], v[152:153]
	v_pk_mul_f32 v[154:155], v[14:15], v[154:155]
	v_pk_mul_f32 v[156:157], v[8:9], v[156:157]
	v_pk_mul_f32 v[158:159], v[10:11], v[158:159]
	v_exp_f32_e32 v152, v152
	v_exp_f32_e32 v153, v153
	v_exp_f32_e32 v154, v154
	v_exp_f32_e32 v155, v155
	v_exp_f32_e32 v156, v156
	v_exp_f32_e32 v157, v157
	v_exp_f32_e32 v158, v158
	v_exp_f32_e32 v159, v159
	v_pk_add_f32 v[168:169], v[168:169], s[64:65]
	v_pk_add_f32 v[170:171], v[170:171], s[64:65]
	v_pk_add_f32 v[172:173], v[172:173], s[64:65]
	v_pk_add_f32 v[174:175], v[174:175], s[64:65]
	v_pk_fma_f32 v[152:153], v[152:153], v[168:169], v[168:169]
	v_pk_fma_f32 v[154:155], v[154:155], v[170:171], v[170:171]
	v_pk_fma_f32 v[156:157], v[156:157], v[172:173], v[172:173]
	v_pk_fma_f32 v[158:159], v[158:159], v[174:175], v[174:175]
	v_pk_mul_f32 v[168:169], v[12:13], v[4:5]
	v_pk_mul_f32 v[170:171], v[14:15], v[6:7]
	v_pk_mul_f32 v[172:173], v[8:9], v[0:1]
	v_pk_mul_f32 v[174:175], v[10:11], v[2:3]
	v_rcp_f32_e32 v152, v152
	v_rcp_f32_e32 v153, v153
	v_rcp_f32_e32 v154, v154
	v_rcp_f32_e32 v155, v155
	v_rcp_f32_e32 v156, v156
	v_rcp_f32_e32 v157, v157
	v_rcp_f32_e32 v158, v158
	v_rcp_f32_e32 v159, v159
	s_nop 0
	v_pk_mul_f32 v[152:153], v[168:169], v[152:153]
	v_pk_mul_f32 v[154:155], v[170:171], v[154:155]
	v_pk_mul_f32 v[156:157], v[172:173], v[156:157]
	v_pk_mul_f32 v[158:159], v[174:175], v[158:159]
	v_cvt_pk_bf16_f32 v180, v152, v153
	v_cvt_pk_bf16_f32 v181, v154, v155
	v_cvt_pk_bf16_f32 v182, v156, v157
	v_cvt_pk_bf16_f32 v183, v158, v159
	global_store_dwordx4 v150, v[180:183], s[24:25]
	s_branch .LBB0_298
.Lp1_epi_m1:
	s_lshl_b32 s14, s59, 9
	s_add_u32 s14, s14, 0x3fff000
	s_add_u32 s24, s24, s14
	s_addc_u32 s25, s25, 0
	v_mov_b32_e32 v151, 0xbdd2d3e8
	v_mov_b32_e32 v148, 0xbdd2d3e8
	v_mov_b32_e32 v149, 0xbdd2d3e8
	v_mov_b32_e32 v160, 0xc0135761
	v_mov_b32_e32 v161, 0xc0135761
	v_pk_mul_f32 v[152:153], v[124:125], v[124:125]
	v_pk_mul_f32 v[154:155], v[126:127], v[126:127]
	v_pk_mul_f32 v[156:157], v[120:121], v[120:121]
	v_pk_mul_f32 v[158:159], v[122:123], v[122:123]
	v_pk_fma_f32 v[152:153], v[148:149], v[152:153], v[160:161]
	v_pk_fma_f32 v[154:155], v[148:149], v[154:155], v[160:161]
	v_pk_fma_f32 v[156:157], v[148:149], v[156:157], v[160:161]
	v_pk_fma_f32 v[158:159], v[148:149], v[158:159], v[160:161]
	v_pk_mul_f32 v[152:153], v[124:125], v[152:153]
	v_pk_mul_f32 v[154:155], v[126:127], v[154:155]
	v_pk_mul_f32 v[156:157], v[120:121], v[156:157]
	v_pk_mul_f32 v[158:159], v[122:123], v[158:159]
	v_exp_f32_e32 v152, v152
	v_exp_f32_e32 v153, v153
	v_exp_f32_e32 v154, v154
	v_exp_f32_e32 v155, v155
	v_exp_f32_e32 v156, v156
	v_exp_f32_e32 v157, v157
	v_exp_f32_e32 v158, v158
	v_exp_f32_e32 v159, v159
	s_nop 0
	v_pk_add_f32 v[152:153], v[152:153], s[64:65]
	v_pk_add_f32 v[154:155], v[154:155], s[64:65]
	v_pk_add_f32 v[156:157], v[156:157], s[64:65]
	v_pk_add_f32 v[158:159], v[158:159], s[64:65]
	v_rcp_f32_e32 v152, v152
	v_rcp_f32_e32 v153, v153
	v_rcp_f32_e32 v154, v154
	v_rcp_f32_e32 v155, v155
	v_rcp_f32_e32 v156, v156
	v_rcp_f32_e32 v157, v157
	v_rcp_f32_e32 v158, v158
	v_rcp_f32_e32 v159, v159
	s_nop 0
	v_pk_mul_f32 v[152:153], v[124:125], v[152:153]
	v_pk_mul_f32 v[154:155], v[126:127], v[154:155]
	v_pk_mul_f32 v[156:157], v[120:121], v[156:157]
	v_pk_mul_f32 v[158:159], v[122:123], v[158:159]
	v_cvt_pk_bf16_f32 v176, v152, v153
	v_cvt_pk_bf16_f32 v177, v154, v155
	v_cvt_pk_bf16_f32 v178, v156, v157
	v_cvt_pk_bf16_f32 v179, v158, v159
	global_store_dwordx4 v150, v[176:179], s[24:25]
	v_pk_mul_f32 v[152:153], v[116:117], v[116:117]
	v_pk_mul_f32 v[154:155], v[118:119], v[118:119]
	v_pk_mul_f32 v[156:157], v[112:113], v[112:113]
	v_pk_mul_f32 v[158:159], v[114:115], v[114:115]
	v_pk_fma_f32 v[152:153], v[148:149], v[152:153], v[160:161]
	v_pk_fma_f32 v[154:155], v[148:149], v[154:155], v[160:161]
	v_pk_fma_f32 v[156:157], v[148:149], v[156:157], v[160:161]
	v_pk_fma_f32 v[158:159], v[148:149], v[158:159], v[160:161]
	v_pk_mul_f32 v[152:153], v[116:117], v[152:153]
	v_pk_mul_f32 v[154:155], v[118:119], v[154:155]
; __device__ __forceinline__ unsigned cvt_pk_bf16(float lo, float hi) { unsigned r; asm volatile("v_cvt_pk_bf16_f32 %0, %1, %2" : "=v"(r) : "v"(lo), "v"(hi)); return r; }
; __device__ __forceinline__ float sigmoid_f(float x) { return __builtin_amdgcn_rcpf(1.0f + __builtin_amdgcn_exp2f(-1.4426950409f * x)); }
;     __device__ __forceinline__ void operator()(f32x4 (&acc)[2][2][4][2], const Unit& u, int wr, int wc, int fr, int fq) const {
;     ...
;                 for (int m = 0; m < 4; ++m) { bf16_t* rowp = O + (size_t)(row0 + ai * HALF + m * 16) * LDP + col0;
; #pragma unroll
;                     for (int bj = 0; bj < 2; ++bj) {
;                         float v[8];
; #pragma unroll
;                         for (int j = 0; j < 4; ++j) { v[j] = acc[ai][bj][m][0][j]; v[4 + j] = acc[ai][bj][m][1][j]; }
;                         if (mode != 0) {
; #pragma unroll
;                             for (int j = 0; j < 8; ++j) {
;                                 const float x = v[j];
;                                 const float a = (mode == 1) ? 1.5957691216f * (x + 0.044715f * x * x * x) : x;
;                                 const float sg = sigmoid_f(a);
;                                 v[j] = (mode == 3) ? sg : x * sg;
;                             }
;                         }
;                         u32x4 w; w.x = cvt_pk_bf16(v[0], v[1]); w.y = cvt_pk_bf16(v[2], v[3]); w.z = cvt_pk_bf16(v[4], v[5]); w.w = cvt_pk_bf16(v[6], v[7]);
;                         *(u32x4*)(rowp + bj * HALF) = w; } }
	v_pk_mul_f32 v[156:157], v[112:113], v[156:157]
	v_pk_mul_f32 v[158:159], v[114:115], v[158:159]
	v_exp_f32_e32 v152, v152
	v_exp_f32_e32 v153, v153
	v_exp_f32_e32 v154, v154
	v_exp_f32_e32 v155, v155
	v_exp_f32_e32 v156, v156
	v_exp_f32_e32 v157, v157
	v_exp_f32_e32 v158, v158
	v_exp_f32_e32 v159, v159
	s_nop 0
	v_pk_add_f32 v[152:153], v[152:153], s[64:65]
	v_pk_add_f32 v[154:155], v[154:155], s[64:65]
	v_pk_add_f32 v[156:157], v[156:157], s[64:65]
	v_pk_add_f32 v[158:159], v[158:159], s[64:65]
	v_rcp_f32_e32 v152, v152
	v_rcp_f32_e32 v153, v153
	v_rcp_f32_e32 v154, v154
	v_rcp_f32_e32 v155, v155
	v_rcp_f32_e32 v156, v156
	v_rcp_f32_e32 v157, v157
	v_rcp_f32_e32 v158, v158
	v_rcp_f32_e32 v159, v159
	s_nop 0
	v_pk_mul_f32 v[152:153], v[116:117], v[152:153]
	v_pk_mul_f32 v[154:155], v[118:119], v[154:155]
	v_pk_mul_f32 v[156:157], v[112:113], v[156:157]
	v_pk_mul_f32 v[158:159], v[114:115], v[158:159]
	v_cvt_pk_bf16_f32 v180, v152, v153
	v_cvt_pk_bf16_f32 v181, v154, v155
	v_cvt_pk_bf16_f32 v182, v156, v157
	v_cvt_pk_bf16_f32 v183, v158, v159
	global_store_dwordx4 v150, v[180:183], s[24:25] offset:256
	s_add_u32 s24, s24, 0x8000
	s_addc_u32 s25, s25, 0
	v_pk_mul_f32 v[152:153], v[108:109], v[108:109]
	v_pk_mul_f32 v[154:155], v[110:111], v[110:111]
	v_pk_mul_f32 v[156:157], v[104:105], v[104:105]
	v_pk_mul_f32 v[158:159], v[106:107], v[106:107]
	v_pk_fma_f32 v[152:153], v[148:149], v[152:153], v[160:161]
	v_pk_fma_f32 v[154:155], v[148:149], v[154:155], v[160:161]
	v_pk_fma_f32 v[156:157], v[148:149], v[156:157], v[160:161]
	v_pk_fma_f32 v[158:159], v[148:149], v[158:159], v[160:161]
	v_pk_mul_f32 v[152:153], v[108:109], v[152:153]
	v_pk_mul_f32 v[154:155], v[110:111], v[154:155]
	v_pk_mul_f32 v[156:157], v[104:105], v[156:157]
	v_pk_mul_f32 v[158:159], v[106:107], v[158:159]
	v_exp_f32_e32 v152, v152
	v_exp_f32_e32 v153, v153
	v_exp_f32_e32 v154, v154
	v_exp_f32_e32 v155, v155
	v_exp_f32_e32 v156, v156
	v_exp_f32_e32 v157, v157
	v_exp_f32_e32 v158, v158
	v_exp_f32_e32 v159, v159
	s_nop 0
	v_pk_add_f32 v[152:153], v[152:153], s[64:65]
	v_pk_add_f32 v[154:155], v[154:155], s[64:65]
	v_pk_add_f32 v[156:157], v[156:157], s[64:65]
	v_pk_add_f32 v[158:159], v[158:159], s[64:65]
	v_rcp_f32_e32 v152, v152
	v_rcp_f32_e32 v153, v153
	v_rcp_f32_e32 v154, v154
	v_rcp_f32_e32 v155, v155
	v_rcp_f32_e32 v156, v156
	v_rcp_f32_e32 v157, v157
	v_rcp_f32_e32 v158, v158
	v_rcp_f32_e32 v159, v159
	s_nop 0
	v_pk_mul_f32 v[152:153], v[108:109], v[152:153]
	v_pk_mul_f32 v[154:155], v[110:111], v[154:155]
	v_pk_mul_f32 v[156:157], v[104:105], v[156:157]
	v_pk_mul_f32 v[158:159], v[106:107], v[158:159]
	v_cvt_pk_bf16_f32 v176, v152, v153
	v_cvt_pk_bf16_f32 v177, v154, v155
	v_cvt_pk_bf16_f32 v178, v156, v157
	v_cvt_pk_bf16_f32 v179, v158, v159
	global_store_dwordx4 v150, v[176:179], s[24:25]
	v_pk_mul_f32 v[152:153], v[100:101], v[100:101]
	v_pk_mul_f32 v[154:155], v[102:103], v[102:103]
	v_pk_mul_f32 v[156:157], v[96:97], v[96:97]
	v_pk_mul_f32 v[158:159], v[98:99], v[98:99]
	v_pk_fma_f32 v[152:153], v[148:149], v[152:153], v[160:161]
	v_pk_fma_f32 v[154:155], v[148:149], v[154:155], v[160:161]
	v_pk_fma_f32 v[156:157], v[148:149], v[156:157], v[160:161]
	v_pk_fma_f32 v[158:159], v[148:149], v[158:159], v[160:161]
	v_pk_mul_f32 v[152:153], v[100:101], v[152:153]
	v_pk_mul_f32 v[154:155], v[102:103], v[154:155]
	v_pk_mul_f32 v[156:157], v[96:97], v[156:157]
	v_pk_mul_f32 v[158:159], v[98:99], v[158:159]
	v_exp_f32_e32 v152, v152
	v_exp_f32_e32 v153, v153
	v_exp_f32_e32 v154, v154
	v_exp_f32_e32 v155, v155
	v_exp_f32_e32 v156, v156
	v_exp_f32_e32 v157, v157
	v_exp_f32_e32 v158, v158
	v_exp_f32_e32 v159, v159
	s_nop 0
	v_pk_add_f32 v[152:153], v[152:153], s[64:65]
	v_pk_add_f32 v[154:155], v[154:155], s[64:65]
	v_pk_add_f32 v[156:157], v[156:157], s[64:65]
	v_pk_add_f32 v[158:159], v[158:159], s[64:65]
	v_rcp_f32_e32 v152, v152
	v_rcp_f32_e32 v153, v153
	v_rcp_f32_e32 v154, v154
	v_rcp_f32_e32 v155, v155
	v_rcp_f32_e32 v156, v156
	v_rcp_f32_e32 v157, v157
	v_rcp_f32_e32 v158, v158
	v_rcp_f32_e32 v159, v159
	s_nop 0
	v_pk_mul_f32 v[152:153], v[100:101], v[152:153]
	v_pk_mul_f32 v[154:155], v[102:103], v[154:155]
	v_pk_mul_f32 v[156:157], v[96:97], v[156:157]
	v_pk_mul_f32 v[158:159], v[98:99], v[158:159]
	v_cvt_pk_bf16_f32 v180, v152, v153
	v_cvt_pk_bf16_f32 v181, v154, v155
	v_cvt_pk_bf16_f32 v182, v156, v157
	v_cvt_pk_bf16_f32 v183, v158, v159
	global_store_dwordx4 v150, v[180:183], s[24:25] offset:256
	s_add_u32 s24, s24, 0x8000
	s_addc_u32 s25, s25, 0
	v_pk_mul_f32 v[152:153], v[92:93], v[92:93]
	v_pk_mul_f32 v[154:155], v[94:95], v[94:95]
	v_pk_mul_f32 v[156:157], v[88:89], v[88:89]
	v_pk_mul_f32 v[158:159], v[90:91], v[90:91]
	v_pk_fma_f32 v[152:153], v[148:149], v[152:153], v[160:161]
	v_pk_fma_f32 v[154:155], v[148:149], v[154:155], v[160:161]
	v_pk_fma_f32 v[156:157], v[148:149], v[156:157], v[160:161]
	v_pk_fma_f32 v[158:159], v[148:149], v[158:159], v[160:161]
	v_pk_mul_f32 v[152:153], v[92:93], v[152:153]
	v_pk_mul_f32 v[154:155], v[94:95], v[154:155]
	v_pk_mul_f32 v[156:157], v[88:89], v[156:157]
	v_pk_mul_f32 v[158:159], v[90:91], v[158:159]
	v_exp_f32_e32 v152, v152
	v_exp_f32_e32 v153, v153
	v_exp_f32_e32 v154, v154
	v_exp_f32_e32 v155, v155
	v_exp_f32_e32 v156, v156
	v_exp_f32_e32 v157, v157
	v_exp_f32_e32 v158, v158
	v_exp_f32_e32 v159, v159
	s_nop 0
	v_pk_add_f32 v[152:153], v[152:153], s[64:65]
	v_pk_add_f32 v[154:155], v[154:155], s[64:65]
	v_pk_add_f32 v[156:157], v[156:157], s[64:65]
	v_pk_add_f32 v[158:159], v[158:159], s[64:65]
	v_rcp_f32_e32 v152, v152
	v_rcp_f32_e32 v153, v153
	v_rcp_f32_e32 v154, v154
	v_rcp_f32_e32 v155, v155
; __device__ __forceinline__ unsigned cvt_pk_bf16(float lo, float hi) { unsigned r; asm volatile("v_cvt_pk_bf16_f32 %0, %1, %2" : "=v"(r) : "v"(lo), "v"(hi)); return r; }
; __device__ __forceinline__ float sigmoid_f(float x) { return __builtin_amdgcn_rcpf(1.0f + __builtin_amdgcn_exp2f(-1.4426950409f * x)); }
;     __device__ __forceinline__ void operator()(f32x4 (&acc)[2][2][4][2], const Unit& u, int wr, int wc, int fr, int fq) const {
;     ...
;                 for (int m = 0; m < 4; ++m) { bf16_t* rowp = O + (size_t)(row0 + ai * HALF + m * 16) * LDP + col0;
; #pragma unroll
;                     for (int bj = 0; bj < 2; ++bj) {
;                         float v[8];
; #pragma unroll
;                         for (int j = 0; j < 4; ++j) { v[j] = acc[ai][bj][m][0][j]; v[4 + j] = acc[ai][bj][m][1][j]; }
;                         if (mode != 0) {
; #pragma unroll
;                             for (int j = 0; j < 8; ++j) {
;                                 const float x = v[j];
;                                 const float a = (mode == 1) ? 1.5957691216f * (x + 0.044715f * x * x * x) : x;
;                                 const float sg = sigmoid_f(a);
;                                 v[j] = (mode == 3) ? sg : x * sg;
;                             }
;                         }
;                         u32x4 w; w.x = cvt_pk_bf16(v[0], v[1]); w.y = cvt_pk_bf16(v[2], v[3]); w.z = cvt_pk_bf16(v[4], v[5]); w.w = cvt_pk_bf16(v[6], v[7]);
;                         *(u32x4*)(rowp + bj * HALF) = w; } }
	v_rcp_f32_e32 v156, v156
	v_rcp_f32_e32 v157, v157
	v_rcp_f32_e32 v158, v158
	v_rcp_f32_e32 v159, v159
	s_nop 0
	v_pk_mul_f32 v[152:153], v[92:93], v[152:153]
	v_pk_mul_f32 v[154:155], v[94:95], v[154:155]
	v_pk_mul_f32 v[156:157], v[88:89], v[156:157]
	v_pk_mul_f32 v[158:159], v[90:91], v[158:159]
	v_cvt_pk_bf16_f32 v176, v152, v153
	v_cvt_pk_bf16_f32 v177, v154, v155
	v_cvt_pk_bf16_f32 v178, v156, v157
	v_cvt_pk_bf16_f32 v179, v158, v159
	global_store_dwordx4 v150, v[176:179], s[24:25]
	v_pk_mul_f32 v[152:153], v[84:85], v[84:85]
	v_pk_mul_f32 v[154:155], v[86:87], v[86:87]
	v_pk_mul_f32 v[156:157], v[80:81], v[80:81]
	v_pk_mul_f32 v[158:159], v[82:83], v[82:83]
	v_pk_fma_f32 v[152:153], v[148:149], v[152:153], v[160:161]
	v_pk_fma_f32 v[154:155], v[148:149], v[154:155], v[160:161]
	v_pk_fma_f32 v[156:157], v[148:149], v[156:157], v[160:161]
	v_pk_fma_f32 v[158:159], v[148:149], v[158:159], v[160:161]
	v_pk_mul_f32 v[152:153], v[84:85], v[152:153]
	v_pk_mul_f32 v[154:155], v[86:87], v[154:155]
	v_pk_mul_f32 v[156:157], v[80:81], v[156:157]
	v_pk_mul_f32 v[158:159], v[82:83], v[158:159]
	v_exp_f32_e32 v152, v152
	v_exp_f32_e32 v153, v153
	v_exp_f32_e32 v154, v154
	v_exp_f32_e32 v155, v155
	v_exp_f32_e32 v156, v156
	v_exp_f32_e32 v157, v157
	v_exp_f32_e32 v158, v158
	v_exp_f32_e32 v159, v159
	s_nop 0
	v_pk_add_f32 v[152:153], v[152:153], s[64:65]
	v_pk_add_f32 v[154:155], v[154:155], s[64:65]
	v_pk_add_f32 v[156:157], v[156:157], s[64:65]
	v_pk_add_f32 v[158:159], v[158:159], s[64:65]
	v_rcp_f32_e32 v152, v152
	v_rcp_f32_e32 v153, v153
	v_rcp_f32_e32 v154, v154
	v_rcp_f32_e32 v155, v155
	v_rcp_f32_e32 v156, v156
	v_rcp_f32_e32 v157, v157
	v_rcp_f32_e32 v158, v158
	v_rcp_f32_e32 v159, v159
	s_nop 0
	v_pk_mul_f32 v[152:153], v[84:85], v[152:153]
	v_pk_mul_f32 v[154:155], v[86:87], v[154:155]
	v_pk_mul_f32 v[156:157], v[80:81], v[156:157]
	v_pk_mul_f32 v[158:159], v[82:83], v[158:159]
	v_cvt_pk_bf16_f32 v180, v152, v153
	v_cvt_pk_bf16_f32 v181, v154, v155
	v_cvt_pk_bf16_f32 v182, v156, v157
	v_cvt_pk_bf16_f32 v183, v158, v159
	global_store_dwordx4 v150, v[180:183], s[24:25] offset:256
	s_add_u32 s24, s24, 0x8000
	s_addc_u32 s25, s25, 0
	v_pk_mul_f32 v[152:153], v[76:77], v[76:77]
	v_pk_mul_f32 v[154:155], v[78:79], v[78:79]
	v_pk_mul_f32 v[156:157], v[72:73], v[72:73]
	v_pk_mul_f32 v[158:159], v[74:75], v[74:75]
	v_pk_fma_f32 v[152:153], v[148:149], v[152:153], v[160:161]
	v_pk_fma_f32 v[154:155], v[148:149], v[154:155], v[160:161]
	v_pk_fma_f32 v[156:157], v[148:149], v[156:157], v[160:161]
	v_pk_fma_f32 v[158:159], v[148:149], v[158:159], v[160:161]
	v_pk_mul_f32 v[152:153], v[76:77], v[152:153]
	v_pk_mul_f32 v[154:155], v[78:79], v[154:155]
	v_pk_mul_f32 v[156:157], v[72:73], v[156:157]
	v_pk_mul_f32 v[158:159], v[74:75], v[158:159]
	v_exp_f32_e32 v152, v152
	v_exp_f32_e32 v153, v153
	v_exp_f32_e32 v154, v154
	v_exp_f32_e32 v155, v155
	v_exp_f32_e32 v156, v156
	v_exp_f32_e32 v157, v157
	v_exp_f32_e32 v158, v158
	v_exp_f32_e32 v159, v159
	s_nop 0
	v_pk_add_f32 v[152:153], v[152:153], s[64:65]
	v_pk_add_f32 v[154:155], v[154:155], s[64:65]
	v_pk_add_f32 v[156:157], v[156:157], s[64:65]
	v_pk_add_f32 v[158:159], v[158:159], s[64:65]
	v_rcp_f32_e32 v152, v152
	v_rcp_f32_e32 v153, v153
	v_rcp_f32_e32 v154, v154
	v_rcp_f32_e32 v155, v155
	v_rcp_f32_e32 v156, v156
	v_rcp_f32_e32 v157, v157
	v_rcp_f32_e32 v158, v158
	v_rcp_f32_e32 v159, v159
	s_nop 0
	v_pk_mul_f32 v[152:153], v[76:77], v[152:153]
	v_pk_mul_f32 v[154:155], v[78:79], v[154:155]
	v_pk_mul_f32 v[156:157], v[72:73], v[156:157]
	v_pk_mul_f32 v[158:159], v[74:75], v[158:159]
	v_cvt_pk_bf16_f32 v176, v152, v153
	v_cvt_pk_bf16_f32 v177, v154, v155
	v_cvt_pk_bf16_f32 v178, v156, v157
	v_cvt_pk_bf16_f32 v179, v158, v159
	global_store_dwordx4 v150, v[176:179], s[24:25]
	v_pk_mul_f32 v[152:153], v[68:69], v[68:69]
	v_pk_mul_f32 v[154:155], v[70:71], v[70:71]
	v_pk_mul_f32 v[156:157], v[64:65], v[64:65]
	v_pk_mul_f32 v[158:159], v[66:67], v[66:67]
	v_pk_fma_f32 v[152:153], v[148:149], v[152:153], v[160:161]
	v_pk_fma_f32 v[154:155], v[148:149], v[154:155], v[160:161]
	v_pk_fma_f32 v[156:157], v[148:149], v[156:157], v[160:161]
	v_pk_fma_f32 v[158:159], v[148:149], v[158:159], v[160:161]
	v_pk_mul_f32 v[152:153], v[68:69], v[152:153]
	v_pk_mul_f32 v[154:155], v[70:71], v[154:155]
	v_pk_mul_f32 v[156:157], v[64:65], v[156:157]
	v_pk_mul_f32 v[158:159], v[66:67], v[158:159]
	v_exp_f32_e32 v152, v152
	v_exp_f32_e32 v153, v153
	v_exp_f32_e32 v154, v154
	v_exp_f32_e32 v155, v155
	v_exp_f32_e32 v156, v156
	v_exp_f32_e32 v157, v157
	v_exp_f32_e32 v158, v158
	v_exp_f32_e32 v159, v159
	s_nop 0
	v_pk_add_f32 v[152:153], v[152:153], s[64:65]
	v_pk_add_f32 v[154:155], v[154:155], s[64:65]
	v_pk_add_f32 v[156:157], v[156:157], s[64:65]
	v_pk_add_f32 v[158:159], v[158:159], s[64:65]
	v_rcp_f32_e32 v152, v152
	v_rcp_f32_e32 v153, v153
	v_rcp_f32_e32 v154, v154
	v_rcp_f32_e32 v155, v155
	v_rcp_f32_e32 v156, v156
	v_rcp_f32_e32 v157, v157
	v_rcp_f32_e32 v158, v158
	v_rcp_f32_e32 v159, v159
	s_nop 0
	v_pk_mul_f32 v[152:153], v[68:69], v[152:153]
	v_pk_mul_f32 v[154:155], v[70:71], v[154:155]
	v_pk_mul_f32 v[156:157], v[64:65], v[156:157]
	v_pk_mul_f32 v[158:159], v[66:67], v[158:159]
	v_cvt_pk_bf16_f32 v180, v152, v153
	v_cvt_pk_bf16_f32 v181, v154, v155
	v_cvt_pk_bf16_f32 v182, v156, v157
	v_cvt_pk_bf16_f32 v183, v158, v159
	global_store_dwordx4 v150, v[180:183], s[24:25] offset:256
	s_add_u32 s24, s24, 0x28000
	s_addc_u32 s25, s25, 0
	v_pk_mul_f32 v[152:153], v[60:61], v[60:61]
	v_pk_mul_f32 v[154:155], v[62:63], v[62:63]
	v_pk_mul_f32 v[156:157], v[56:57], v[56:57]
	v_pk_mul_f32 v[158:159], v[58:59], v[58:59]
; __device__ __forceinline__ unsigned cvt_pk_bf16(float lo, float hi) { unsigned r; asm volatile("v_cvt_pk_bf16_f32 %0, %1, %2" : "=v"(r) : "v"(lo), "v"(hi)); return r; }
; __device__ __forceinline__ float sigmoid_f(float x) { return __builtin_amdgcn_rcpf(1.0f + __builtin_amdgcn_exp2f(-1.4426950409f * x)); }
;     __device__ __forceinline__ void operator()(f32x4 (&acc)[2][2][4][2], const Unit& u, int wr, int wc, int fr, int fq) const {
;     ...
;                 for (int m = 0; m < 4; ++m) { bf16_t* rowp = O + (size_t)(row0 + ai * HALF + m * 16) * LDP + col0;
; #pragma unroll
;                     for (int bj = 0; bj < 2; ++bj) {
;                         float v[8];
; #pragma unroll
;                         for (int j = 0; j < 4; ++j) { v[j] = acc[ai][bj][m][0][j]; v[4 + j] = acc[ai][bj][m][1][j]; }
;                         if (mode != 0) {
; #pragma unroll
;                             for (int j = 0; j < 8; ++j) {
;                                 const float x = v[j];
;                                 const float a = (mode == 1) ? 1.5957691216f * (x + 0.044715f * x * x * x) : x;
;                                 const float sg = sigmoid_f(a);
;                                 v[j] = (mode == 3) ? sg : x * sg;
;                             }
;                         }
;                         u32x4 w; w.x = cvt_pk_bf16(v[0], v[1]); w.y = cvt_pk_bf16(v[2], v[3]); w.z = cvt_pk_bf16(v[4], v[5]); w.w = cvt_pk_bf16(v[6], v[7]);
;                         *(u32x4*)(rowp + bj * HALF) = w; } }
	v_pk_fma_f32 v[152:153], v[148:149], v[152:153], v[160:161]
	v_pk_fma_f32 v[154:155], v[148:149], v[154:155], v[160:161]
	v_pk_fma_f32 v[156:157], v[148:149], v[156:157], v[160:161]
	v_pk_fma_f32 v[158:159], v[148:149], v[158:159], v[160:161]
	v_pk_mul_f32 v[152:153], v[60:61], v[152:153]
	v_pk_mul_f32 v[154:155], v[62:63], v[154:155]
	v_pk_mul_f32 v[156:157], v[56:57], v[156:157]
	v_pk_mul_f32 v[158:159], v[58:59], v[158:159]
	v_exp_f32_e32 v152, v152
	v_exp_f32_e32 v153, v153
	v_exp_f32_e32 v154, v154
	v_exp_f32_e32 v155, v155
	v_exp_f32_e32 v156, v156
	v_exp_f32_e32 v157, v157
	v_exp_f32_e32 v158, v158
	v_exp_f32_e32 v159, v159
	s_nop 0
	v_pk_add_f32 v[152:153], v[152:153], s[64:65]
	v_pk_add_f32 v[154:155], v[154:155], s[64:65]
	v_pk_add_f32 v[156:157], v[156:157], s[64:65]
	v_pk_add_f32 v[158:159], v[158:159], s[64:65]
	v_rcp_f32_e32 v152, v152
	v_rcp_f32_e32 v153, v153
	v_rcp_f32_e32 v154, v154
	v_rcp_f32_e32 v155, v155
	v_rcp_f32_e32 v156, v156
	v_rcp_f32_e32 v157, v157
	v_rcp_f32_e32 v158, v158
	v_rcp_f32_e32 v159, v159
	s_nop 0
	v_pk_mul_f32 v[152:153], v[60:61], v[152:153]
	v_pk_mul_f32 v[154:155], v[62:63], v[154:155]
	v_pk_mul_f32 v[156:157], v[56:57], v[156:157]
	v_pk_mul_f32 v[158:159], v[58:59], v[158:159]
	v_cvt_pk_bf16_f32 v176, v152, v153
	v_cvt_pk_bf16_f32 v177, v154, v155
	v_cvt_pk_bf16_f32 v178, v156, v157
	v_cvt_pk_bf16_f32 v179, v158, v159
	global_store_dwordx4 v150, v[176:179], s[24:25]
	v_pk_mul_f32 v[152:153], v[52:53], v[52:53]
	v_pk_mul_f32 v[154:155], v[54:55], v[54:55]
	v_pk_mul_f32 v[156:157], v[48:49], v[48:49]
	v_pk_mul_f32 v[158:159], v[50:51], v[50:51]
	v_pk_fma_f32 v[152:153], v[148:149], v[152:153], v[160:161]
	v_pk_fma_f32 v[154:155], v[148:149], v[154:155], v[160:161]
	v_pk_fma_f32 v[156:157], v[148:149], v[156:157], v[160:161]
	v_pk_fma_f32 v[158:159], v[148:149], v[158:159], v[160:161]
	v_pk_mul_f32 v[152:153], v[52:53], v[152:153]
	v_pk_mul_f32 v[154:155], v[54:55], v[154:155]
	v_pk_mul_f32 v[156:157], v[48:49], v[156:157]
	v_pk_mul_f32 v[158:159], v[50:51], v[158:159]
	v_exp_f32_e32 v152, v152
	v_exp_f32_e32 v153, v153
	v_exp_f32_e32 v154, v154
	v_exp_f32_e32 v155, v155
	v_exp_f32_e32 v156, v156
	v_exp_f32_e32 v157, v157
	v_exp_f32_e32 v158, v158
	v_exp_f32_e32 v159, v159
	s_nop 0
	v_pk_add_f32 v[152:153], v[152:153], s[64:65]
	v_pk_add_f32 v[154:155], v[154:155], s[64:65]
	v_pk_add_f32 v[156:157], v[156:157], s[64:65]
	v_pk_add_f32 v[158:159], v[158:159], s[64:65]
	v_rcp_f32_e32 v152, v152
	v_rcp_f32_e32 v153, v153
	v_rcp_f32_e32 v154, v154
	v_rcp_f32_e32 v155, v155
	v_rcp_f32_e32 v156, v156
	v_rcp_f32_e32 v157, v157
	v_rcp_f32_e32 v158, v158
	v_rcp_f32_e32 v159, v159
	s_nop 0
	v_pk_mul_f32 v[152:153], v[52:53], v[152:153]
	v_pk_mul_f32 v[154:155], v[54:55], v[154:155]
	v_pk_mul_f32 v[156:157], v[48:49], v[156:157]
	v_pk_mul_f32 v[158:159], v[50:51], v[158:159]
	v_cvt_pk_bf16_f32 v180, v152, v153
	v_cvt_pk_bf16_f32 v181, v154, v155
	v_cvt_pk_bf16_f32 v182, v156, v157
	v_cvt_pk_bf16_f32 v183, v158, v159
	global_store_dwordx4 v150, v[180:183], s[24:25] offset:256
	s_add_u32 s24, s24, 0x8000
	s_addc_u32 s25, s25, 0
	v_pk_mul_f32 v[152:153], v[44:45], v[44:45]
	v_pk_mul_f32 v[154:155], v[46:47], v[46:47]
	v_pk_mul_f32 v[156:157], v[40:41], v[40:41]
	v_pk_mul_f32 v[158:159], v[42:43], v[42:43]
	v_pk_fma_f32 v[152:153], v[148:149], v[152:153], v[160:161]
	v_pk_fma_f32 v[154:155], v[148:149], v[154:155], v[160:161]
	v_pk_fma_f32 v[156:157], v[148:149], v[156:157], v[160:161]
	v_pk_fma_f32 v[158:159], v[148:149], v[158:159], v[160:161]
	v_pk_mul_f32 v[152:153], v[44:45], v[152:153]
	v_pk_mul_f32 v[154:155], v[46:47], v[154:155]
	v_pk_mul_f32 v[156:157], v[40:41], v[156:157]
	v_pk_mul_f32 v[158:159], v[42:43], v[158:159]
	v_exp_f32_e32 v152, v152
	v_exp_f32_e32 v153, v153
	v_exp_f32_e32 v154, v154
	v_exp_f32_e32 v155, v155
	v_exp_f32_e32 v156, v156
	v_exp_f32_e32 v157, v157
	v_exp_f32_e32 v158, v158
	v_exp_f32_e32 v159, v159
	s_nop 0
	v_pk_add_f32 v[152:153], v[152:153], s[64:65]
	v_pk_add_f32 v[154:155], v[154:155], s[64:65]
	v_pk_add_f32 v[156:157], v[156:157], s[64:65]
	v_pk_add_f32 v[158:159], v[158:159], s[64:65]
	v_rcp_f32_e32 v152, v152
	v_rcp_f32_e32 v153, v153
	v_rcp_f32_e32 v154, v154
	v_rcp_f32_e32 v155, v155
	v_rcp_f32_e32 v156, v156
	v_rcp_f32_e32 v157, v157
	v_rcp_f32_e32 v158, v158
	v_rcp_f32_e32 v159, v159
	s_nop 0
	v_pk_mul_f32 v[152:153], v[44:45], v[152:153]
	v_pk_mul_f32 v[154:155], v[46:47], v[154:155]
	v_pk_mul_f32 v[156:157], v[40:41], v[156:157]
	v_pk_mul_f32 v[158:159], v[42:43], v[158:159]
	v_cvt_pk_bf16_f32 v176, v152, v153
	v_cvt_pk_bf16_f32 v177, v154, v155
	v_cvt_pk_bf16_f32 v178, v156, v157
	v_cvt_pk_bf16_f32 v179, v158, v159
	global_store_dwordx4 v150, v[176:179], s[24:25]
	v_pk_mul_f32 v[152:153], v[36:37], v[36:37]
	v_pk_mul_f32 v[154:155], v[38:39], v[38:39]
	v_pk_mul_f32 v[156:157], v[32:33], v[32:33]
	v_pk_mul_f32 v[158:159], v[34:35], v[34:35]
	v_pk_fma_f32 v[152:153], v[148:149], v[152:153], v[160:161]
	v_pk_fma_f32 v[154:155], v[148:149], v[154:155], v[160:161]
	v_pk_fma_f32 v[156:157], v[148:149], v[156:157], v[160:161]
	v_pk_fma_f32 v[158:159], v[148:149], v[158:159], v[160:161]
	v_pk_mul_f32 v[152:153], v[36:37], v[152:153]
	v_pk_mul_f32 v[154:155], v[38:39], v[154:155]
	v_pk_mul_f32 v[156:157], v[32:33], v[156:157]
	v_pk_mul_f32 v[158:159], v[34:35], v[158:159]
	v_exp_f32_e32 v152, v152
	v_exp_f32_e32 v153, v153
	v_exp_f32_e32 v154, v154
	v_exp_f32_e32 v155, v155
	v_exp_f32_e32 v156, v156
	v_exp_f32_e32 v157, v157
	v_exp_f32_e32 v158, v158
	v_exp_f32_e32 v159, v159
	s_nop 0
	v_pk_add_f32 v[152:153], v[152:153], s[64:65]
	v_pk_add_f32 v[154:155], v[154:155], s[64:65]
; __device__ __forceinline__ unsigned cvt_pk_bf16(float lo, float hi) { unsigned r; asm volatile("v_cvt_pk_bf16_f32 %0, %1, %2" : "=v"(r) : "v"(lo), "v"(hi)); return r; }
; __device__ __forceinline__ float sigmoid_f(float x) { return __builtin_amdgcn_rcpf(1.0f + __builtin_amdgcn_exp2f(-1.4426950409f * x)); }
;     __device__ __forceinline__ void operator()(f32x4 (&acc)[2][2][4][2], const Unit& u, int wr, int wc, int fr, int fq) const {
;     ...
;                 for (int m = 0; m < 4; ++m) { bf16_t* rowp = O + (size_t)(row0 + ai * HALF + m * 16) * LDP + col0;
; #pragma unroll
;                     for (int bj = 0; bj < 2; ++bj) {
;                         float v[8];
; #pragma unroll
;                         for (int j = 0; j < 4; ++j) { v[j] = acc[ai][bj][m][0][j]; v[4 + j] = acc[ai][bj][m][1][j]; }
;                         if (mode != 0) {
; #pragma unroll
;                             for (int j = 0; j < 8; ++j) {
;                                 const float x = v[j];
;                                 const float a = (mode == 1) ? 1.5957691216f * (x + 0.044715f * x * x * x) : x;
;                                 const float sg = sigmoid_f(a);
;                                 v[j] = (mode == 3) ? sg : x * sg;
;                             }
;                         }
;                         u32x4 w; w.x = cvt_pk_bf16(v[0], v[1]); w.y = cvt_pk_bf16(v[2], v[3]); w.z = cvt_pk_bf16(v[4], v[5]); w.w = cvt_pk_bf16(v[6], v[7]);
;                         *(u32x4*)(rowp + bj * HALF) = w; } }
	v_pk_add_f32 v[156:157], v[156:157], s[64:65]
	v_pk_add_f32 v[158:159], v[158:159], s[64:65]
	v_rcp_f32_e32 v152, v152
	v_rcp_f32_e32 v153, v153
	v_rcp_f32_e32 v154, v154
	v_rcp_f32_e32 v155, v155
	v_rcp_f32_e32 v156, v156
	v_rcp_f32_e32 v157, v157
	v_rcp_f32_e32 v158, v158
	v_rcp_f32_e32 v159, v159
	s_nop 0
	v_pk_mul_f32 v[152:153], v[36:37], v[152:153]
	v_pk_mul_f32 v[154:155], v[38:39], v[154:155]
	v_pk_mul_f32 v[156:157], v[32:33], v[156:157]
	v_pk_mul_f32 v[158:159], v[34:35], v[158:159]
	v_cvt_pk_bf16_f32 v180, v152, v153
	v_cvt_pk_bf16_f32 v181, v154, v155
	v_cvt_pk_bf16_f32 v182, v156, v157
	v_cvt_pk_bf16_f32 v183, v158, v159
	global_store_dwordx4 v150, v[180:183], s[24:25] offset:256
	s_add_u32 s24, s24, 0x8000
	s_addc_u32 s25, s25, 0
	v_pk_mul_f32 v[152:153], v[28:29], v[28:29]
	v_pk_mul_f32 v[154:155], v[30:31], v[30:31]
	v_pk_mul_f32 v[156:157], v[24:25], v[24:25]
	v_pk_mul_f32 v[158:159], v[26:27], v[26:27]
	v_pk_fma_f32 v[152:153], v[148:149], v[152:153], v[160:161]
	v_pk_fma_f32 v[154:155], v[148:149], v[154:155], v[160:161]
	v_pk_fma_f32 v[156:157], v[148:149], v[156:157], v[160:161]
	v_pk_fma_f32 v[158:159], v[148:149], v[158:159], v[160:161]
	v_pk_mul_f32 v[152:153], v[28:29], v[152:153]
	v_pk_mul_f32 v[154:155], v[30:31], v[154:155]
	v_pk_mul_f32 v[156:157], v[24:25], v[156:157]
	v_pk_mul_f32 v[158:159], v[26:27], v[158:159]
	v_exp_f32_e32 v152, v152
	v_exp_f32_e32 v153, v153
	v_exp_f32_e32 v154, v154
	v_exp_f32_e32 v155, v155
	v_exp_f32_e32 v156, v156
	v_exp_f32_e32 v157, v157
	v_exp_f32_e32 v158, v158
	v_exp_f32_e32 v159, v159
	s_nop 0
	v_pk_add_f32 v[152:153], v[152:153], s[64:65]
	v_pk_add_f32 v[154:155], v[154:155], s[64:65]
	v_pk_add_f32 v[156:157], v[156:157], s[64:65]
	v_pk_add_f32 v[158:159], v[158:159], s[64:65]
	v_rcp_f32_e32 v152, v152
	v_rcp_f32_e32 v153, v153
	v_rcp_f32_e32 v154, v154
	v_rcp_f32_e32 v155, v155
	v_rcp_f32_e32 v156, v156
	v_rcp_f32_e32 v157, v157
	v_rcp_f32_e32 v158, v158
	v_rcp_f32_e32 v159, v159
	s_nop 0
	v_pk_mul_f32 v[152:153], v[28:29], v[152:153]
	v_pk_mul_f32 v[154:155], v[30:31], v[154:155]
	v_pk_mul_f32 v[156:157], v[24:25], v[156:157]
	v_pk_mul_f32 v[158:159], v[26:27], v[158:159]
	v_cvt_pk_bf16_f32 v176, v152, v153
	v_cvt_pk_bf16_f32 v177, v154, v155
	v_cvt_pk_bf16_f32 v178, v156, v157
	v_cvt_pk_bf16_f32 v179, v158, v159
	global_store_dwordx4 v150, v[176:179], s[24:25]
	v_pk_mul_f32 v[152:153], v[20:21], v[20:21]
	v_pk_mul_f32 v[154:155], v[22:23], v[22:23]
	v_pk_mul_f32 v[156:157], v[16:17], v[16:17]
	v_pk_mul_f32 v[158:159], v[18:19], v[18:19]
	v_pk_fma_f32 v[152:153], v[148:149], v[152:153], v[160:161]
	v_pk_fma_f32 v[154:155], v[148:149], v[154:155], v[160:161]
	v_pk_fma_f32 v[156:157], v[148:149], v[156:157], v[160:161]
	v_pk_fma_f32 v[158:159], v[148:149], v[158:159], v[160:161]
	v_pk_mul_f32 v[152:153], v[20:21], v[152:153]
	v_pk_mul_f32 v[154:155], v[22:23], v[154:155]
	v_pk_mul_f32 v[156:157], v[16:17], v[156:157]
	v_pk_mul_f32 v[158:159], v[18:19], v[158:159]
	v_exp_f32_e32 v152, v152
	v_exp_f32_e32 v153, v153
	v_exp_f32_e32 v154, v154
	v_exp_f32_e32 v155, v155
	v_exp_f32_e32 v156, v156
	v_exp_f32_e32 v157, v157
	v_exp_f32_e32 v158, v158
	v_exp_f32_e32 v159, v159
	s_nop 0
	v_pk_add_f32 v[152:153], v[152:153], s[64:65]
	v_pk_add_f32 v[154:155], v[154:155], s[64:65]
	v_pk_add_f32 v[156:157], v[156:157], s[64:65]
	v_pk_add_f32 v[158:159], v[158:159], s[64:65]
	v_rcp_f32_e32 v152, v152
	v_rcp_f32_e32 v153, v153
	v_rcp_f32_e32 v154, v154
	v_rcp_f32_e32 v155, v155
	v_rcp_f32_e32 v156, v156
	v_rcp_f32_e32 v157, v157
	v_rcp_f32_e32 v158, v158
	v_rcp_f32_e32 v159, v159
	s_nop 0
	v_pk_mul_f32 v[152:153], v[20:21], v[152:153]
; __device__ __forceinline__ unsigned cvt_pk_bf16(float lo, float hi) { unsigned r; asm volatile("v_cvt_pk_bf16_f32 %0, %1, %2" : "=v"(r) : "v"(lo), "v"(hi)); return r; }
; __device__ __forceinline__ float sigmoid_f(float x) { return __builtin_amdgcn_rcpf(1.0f + __builtin_amdgcn_exp2f(-1.4426950409f * x)); }
;     __device__ __forceinline__ void operator()(f32x4 (&acc)[2][2][4][2], const Unit& u, int wr, int wc, int fr, int fq) const {
;     ...
;                 for (int m = 0; m < 4; ++m) { bf16_t* rowp = O + (size_t)(row0 + ai * HALF + m * 16) * LDP + col0;
; #pragma unroll
;                     for (int bj = 0; bj < 2; ++bj) {
;                         float v[8];
; #pragma unroll
;                         for (int j = 0; j < 4; ++j) { v[j] = acc[ai][bj][m][0][j]; v[4 + j] = acc[ai][bj][m][1][j]; }
;                         if (mode != 0) {
; #pragma unroll
;                             for (int j = 0; j < 8; ++j) {
;                                 const float x = v[j];
;                                 const float a = (mode == 1) ? 1.5957691216f * (x + 0.044715f * x * x * x) : x;
;                                 const float sg = sigmoid_f(a);
;                                 v[j] = (mode == 3) ? sg : x * sg;
;                             }
;                         }
;                         u32x4 w; w.x = cvt_pk_bf16(v[0], v[1]); w.y = cvt_pk_bf16(v[2], v[3]); w.z = cvt_pk_bf16(v[4], v[5]); w.w = cvt_pk_bf16(v[6], v[7]);
;                         *(u32x4*)(rowp + bj * HALF) = w; } }
	v_pk_mul_f32 v[154:155], v[22:23], v[154:155]
	v_pk_mul_f32 v[156:157], v[16:17], v[156:157]
	v_pk_mul_f32 v[158:159], v[18:19], v[158:159]
	v_cvt_pk_bf16_f32 v180, v152, v153
	v_cvt_pk_bf16_f32 v181, v154, v155
	v_cvt_pk_bf16_f32 v182, v156, v157
	v_cvt_pk_bf16_f32 v183, v158, v159
	global_store_dwordx4 v150, v[180:183], s[24:25] offset:256
	s_add_u32 s24, s24, 0x8000
	s_addc_u32 s25, s25, 0
	v_pk_mul_f32 v[152:153], v[12:13], v[12:13]
	v_pk_mul_f32 v[154:155], v[14:15], v[14:15]
	v_pk_mul_f32 v[156:157], v[8:9], v[8:9]
	v_pk_mul_f32 v[158:159], v[10:11], v[10:11]
	v_pk_fma_f32 v[152:153], v[148:149], v[152:153], v[160:161]
	v_pk_fma_f32 v[154:155], v[148:149], v[154:155], v[160:161]
	v_pk_fma_f32 v[156:157], v[148:149], v[156:157], v[160:161]
	v_pk_fma_f32 v[158:159], v[148:149], v[158:159], v[160:161]
	v_pk_mul_f32 v[152:153], v[12:13], v[152:153]
	v_pk_mul_f32 v[154:155], v[14:15], v[154:155]
	v_pk_mul_f32 v[156:157], v[8:9], v[156:157]
	v_pk_mul_f32 v[158:159], v[10:11], v[158:159]
	v_exp_f32_e32 v152, v152
	v_exp_f32_e32 v153, v153
	v_exp_f32_e32 v154, v154
	v_exp_f32_e32 v155, v155
	v_exp_f32_e32 v156, v156
	v_exp_f32_e32 v157, v157
	v_exp_f32_e32 v158, v158
	v_exp_f32_e32 v159, v159
	s_nop 0
	v_pk_add_f32 v[152:153], v[152:153], s[64:65]
	v_pk_add_f32 v[154:155], v[154:155], s[64:65]
	v_pk_add_f32 v[156:157], v[156:157], s[64:65]
	v_pk_add_f32 v[158:159], v[158:159], s[64:65]
	v_rcp_f32_e32 v152, v152
	v_rcp_f32_e32 v153, v153
	v_rcp_f32_e32 v154, v154
	v_rcp_f32_e32 v155, v155
	v_rcp_f32_e32 v156, v156
	v_rcp_f32_e32 v157, v157
	v_rcp_f32_e32 v158, v158
	v_rcp_f32_e32 v159, v159
	s_nop 0
	v_pk_mul_f32 v[152:153], v[12:13], v[152:153]
	v_pk_mul_f32 v[154:155], v[14:15], v[154:155]
	v_pk_mul_f32 v[156:157], v[8:9], v[156:157]
	v_pk_mul_f32 v[158:159], v[10:11], v[158:159]
	v_cvt_pk_bf16_f32 v176, v152, v153
	v_cvt_pk_bf16_f32 v177, v154, v155
	v_cvt_pk_bf16_f32 v178, v156, v157
	v_cvt_pk_bf16_f32 v179, v158, v159
	global_store_dwordx4 v150, v[176:179], s[24:25]
	v_pk_mul_f32 v[152:153], v[4:5], v[4:5]
	v_pk_mul_f32 v[154:155], v[6:7], v[6:7]
	v_pk_mul_f32 v[156:157], v[0:1], v[0:1]
	v_pk_mul_f32 v[158:159], v[2:3], v[2:3]
	v_pk_fma_f32 v[152:153], v[148:149], v[152:153], v[160:161]
	v_pk_fma_f32 v[154:155], v[148:149], v[154:155], v[160:161]
	v_pk_fma_f32 v[156:157], v[148:149], v[156:157], v[160:161]
	v_pk_fma_f32 v[158:159], v[148:149], v[158:159], v[160:161]
	v_pk_mul_f32 v[152:153], v[4:5], v[152:153]
	v_pk_mul_f32 v[154:155], v[6:7], v[154:155]
	v_pk_mul_f32 v[156:157], v[0:1], v[156:157]
	v_pk_mul_f32 v[158:159], v[2:3], v[158:159]
	v_exp_f32_e32 v152, v152
	v_exp_f32_e32 v153, v153
	v_exp_f32_e32 v154, v154
	v_exp_f32_e32 v155, v155
	v_exp_f32_e32 v156, v156
	v_exp_f32_e32 v157, v157
	v_exp_f32_e32 v158, v158
	v_exp_f32_e32 v159, v159
	s_nop 0
	v_pk_add_f32 v[152:153], v[152:153], s[64:65]
	v_pk_add_f32 v[154:155], v[154:155], s[64:65]
	v_pk_add_f32 v[156:157], v[156:157], s[64:65]
	v_pk_add_f32 v[158:159], v[158:159], s[64:65]
	v_rcp_f32_e32 v152, v152
	v_rcp_f32_e32 v153, v153
	v_rcp_f32_e32 v154, v154
	v_rcp_f32_e32 v155, v155
	v_rcp_f32_e32 v156, v156
	v_rcp_f32_e32 v157, v157
	v_rcp_f32_e32 v158, v158
	v_rcp_f32_e32 v159, v159
	s_nop 0
	v_pk_mul_f32 v[152:153], v[4:5], v[152:153]
	v_pk_mul_f32 v[154:155], v[6:7], v[154:155]
	v_pk_mul_f32 v[156:157], v[0:1], v[156:157]
	v_pk_mul_f32 v[158:159], v[2:3], v[158:159]
	v_cvt_pk_bf16_f32 v180, v152, v153
	v_cvt_pk_bf16_f32 v181, v154, v155
	v_cvt_pk_bf16_f32 v182, v156, v157
	v_cvt_pk_bf16_f32 v183, v158, v159
	global_store_dwordx4 v150, v[180:183], s[24:25] offset:256
	s_branch .LBB0_298
